# init_phase 12 loads in flight; convert (k=0 path) touches the tile two iterations ahead (L2 warming)
# baseline (speedup 1.0000x reference)
; __device__ __forceinline__ void refresh(Frame& F) { int t = threadIdx.x; asm volatile("" : "+v"(t)); F.tid = t; F.lane = t & 63; F.wave = __builtin_amdgcn_readfirstlane(t >> 6); }
; __device__ __forceinline__ void cvt_load(const Frame& F, const CvtMat& m, int tt, f32x4 (&v)[4]) {
;     const int nb = m.N >> 7, kb = tt / nb, nbk = tt - kb * nb, k0 = kb * 64, n0 = nbk * 128;
;     const int src = srccol(m.kind, n0 + (F.tid & 31) * 4);
; #pragma unroll
;     for (int i = 0; i < 4; ++i) v[i] = *(const f32x4*)(m.W + (size_t)(k0 + (F.tid >> 5) + 16 * i) * m.N + src);
; }
; __device__ __forceinline__ void convert_layer(const Args& A, Frame& F, int l) {
;     refresh(F);
;     constexpr int NT = 2 * 16 * 44 + 2 * 44 * 8 + 16 * 56 + 3 * 16 * 8;
;     const int nmy = (NT - F.bid + F.G - 1) / F.G;
;     f32x4 v[4];
;     { CvtMat m; int tt; cvt_pick(A, F, l, F.bid, m, tt); cvt_load(F, m, tt, v); }
;     for (int j = 0; j < nmy; ++j) {
;         const int it = F.bid + j * F.G, itn = (j + 1 < nmy) ? it + F.G : it;
;         f32x4 vn[4];
;         { CvtMat mn; int ttn; cvt_pick(A, F, l, itn, mn, ttn); cvt_load(F, mn, ttn, vn); }
.LBB0_605:
	s_abs_i32 s2, s34
	v_cvt_f32_u32_e32 v3, s2
	s_sub_i32 s10, s34, s38
	s_add_i32 s11, s10, 0xd3f
	s_sub_i32 s10, 0xfffff2c1, s10
	v_rcp_iflag_f32_e32 v3, v3
	s_xor_b32 s13, s11, s34
	s_sub_i32 s12, 0, s2
	s_max_i32 s10, s11, s10
	v_mul_f32_e32 v3, 0x4f7ffffe, v3
	v_cvt_u32_f32_e32 v3, v3
	s_ashr_i32 s11, s13, 31
	v_readfirstlane_b32 s13, v3
	s_mul_i32 s12, s12, s13
	s_mul_hi_u32 s12, s13, s12
	s_add_i32 s13, s13, s12
	s_mul_hi_u32 s12, s10, s13
	s_mul_i32 s13, s12, s2
	s_sub_i32 s10, s10, s13
	s_add_i32 s15, s12, 1
	s_sub_i32 s13, s10, s2
	s_cmp_ge_u32 s10, s2
	s_cselect_b32 s12, s15, s12
	s_cselect_b32 s10, s13, s10
	s_add_i32 s13, s12, 1
	s_cmp_ge_u32 s10, s2
	s_cselect_b32 s2, s13, s12
	s_xor_b32 s2, s2, s11
	s_sub_i32 s2, s2, s11
	s_cmp_lt_i32 s2, 1
	s_cbranch_scc1 .LBB0_691
	s_mul_hi_u32 s11, s4, s44
	s_mul_i32 s10, s4, s44
	s_lshl_b64 s[10:11], s[10:11], 2
	v_ashrrev_i32_e32 v35, 5, v0
	s_waitcnt lgkmcnt(0)
	s_add_u32 s8, s8, s10
	v_lshl_add_u32 v14, s14, 6, v35
	s_addc_u32 s9, s9, s11
	v_mad_i64_i32 v[4:5], s[10:11], v14, s5, 0
	v_ashrrev_i32_e32 v3, 31, v2
	v_lshl_add_u64 v[4:5], v[4:5], 2, s[8:9]
	v_lshlrev_b64 v[10:11], 2, v[2:3]
	v_lshl_add_u64 v[2:3], v[4:5], 0, v[10:11]
	v_add_u32_e32 v4, 16, v14
	v_add_u32_e32 v12, 32, v14
	v_add_u32_e32 v14, 48, v14
	v_mad_i64_i32 v[4:5], s[10:11], s5, v4, 0
	v_mad_i64_i32 v[12:13], s[10:11], s5, v12, 0
	v_mad_i64_i32 v[14:15], s[4:5], s5, v14, 0
	v_lshl_add_u64 v[4:5], v[4:5], 2, s[8:9]
	v_lshl_add_u64 v[12:13], v[12:13], 2, s[8:9]
	v_lshl_add_u64 v[14:15], v[14:15], 2, s[8:9]
	v_lshl_add_u64 v[6:7], v[4:5], 0, v[10:11]
	v_lshl_add_u64 v[12:13], v[12:13], 0, v[10:11]
	v_lshl_add_u64 v[14:15], v[14:15], 0, v[10:11]
	global_load_dwordx4 v[2:5], v[2:3], off
	s_nop 0
	global_load_dwordx4 v[6:9], v[6:7], off
	s_nop 0
	global_load_dwordx4 v[10:13], v[12:13], off
	s_nop 0
	global_load_dwordx4 v[14:17], v[14:15], off
	v_lshlrev_b32_e32 v22, 4, v0
	v_and_b32_e32 v22, 48, v22
	v_ashrrev_i32_e32 v36, 2, v0
	v_mul_u32_u24_e32 v25, 0x204, v22
	v_and_b32_e32 v0, -4, v0
	v_add3_u32 v37, 0, v25, v0
	v_lshrrev_b32_e32 v0, 1, v18
	s_movk_i32 s4, 0x204
	v_and_b32_e32 v0, 16, v0
	v_lshl_add_u32 v23, v34, 2, 0
	v_mul_lo_u32 v24, v35, s4
	v_and_or_b32 v38, v21, 32, v0
	v_and_b32_e32 v0, 0x60, v18
	v_or_b32_e32 v39, v20, v19
	v_or3_b32 v40, v0, v19, v20
	s_mov_b32 s20, 0
	v_add_u32_e32 v41, v23, v24
	v_lshlrev_b32_e32 v0, 1, v22
	s_mov_b32 s26, s38
	s_waitcnt vmcnt(0)
	s_branch .LBB0_608
; __device__ __forceinline__ void cvt_pick(const Args& A, const Frame& F, int l, int it, CvtMat& m, int& tt) {
;     constexpr int T_GU = 16 * 44, T_D = 44 * 8, T_IN = 16 * 56, T_SQ = 16 * 8;
;     constexpr int O1 = T_GU, O2 = O1 + T_D, O3 = O2 + T_GU, O4 = O3 + T_D, O5 = O4 + T_IN, O6 = O5 + T_SQ, O7 = O6 + T_SQ;
;     const int sel = (it >= O1) + (it >= O2) + (it >= O3) + (it >= O4) + (it >= O5) + (it >= O6) + (it >= O7);
;     const int inidx = sel == 0 ? 7 : sel == 1 ? 8 : sel == 2 ? 9 : sel == 3 ? 10 : sel == 4 ? 11 : sel == 5 ? 13 : sel == 6 ? 19 : 20;
; __device__ __forceinline__ void cvt_store(const Frame& F, const CvtMat& m, int tt, const f32x4 (&v)[4]) {
;     LAS float* tile = (LAS float*)F.lds;
;     const int nb = m.N >> 7, kb = tt / nb, nbk = tt - kb * nb, k0 = kb * 64, n0 = nbk * 128;
;     const int tid = F.tid;
; #pragma unroll
;     for (int i = 0; i < 4; ++i) {
;         const int kk = (tid >> 5) + 16 * i, nn = (tid & 31) * 4;
;         tile[kk * 129 + nn] = v[i][0]; tile[kk * 129 + nn + 1] = v[i][1]; tile[kk * 129 + nn + 2] = v[i][2]; tile[kk * 129 + nn + 3] = v[i][3];
;     }
;     __syncthreads();
;     {
;         const int n = tid >> 2, ks = (tid & 3) * 16;
;         u32x4 o0, o1;
; #pragma unroll
;         for (int i = 0; i < 4; ++i) o0[i] = pk2(tile[(ks + 2 * i) * 129 + n], tile[(ks + 2 * i + 1) * 129 + n]);
; #pragma unroll
;         for (int i = 0; i < 4; ++i) o1[i] = pk2(tile[(ks + 8 + 2 * i) * 129 + n], tile[(ks + 8 + 2 * i + 1) * 129 + n]);
;         bf16_t* dst = m.Bt + (size_t)(n0 + n) * m.K + k0 + ks;
;         *(u32x4*)dst = o0; *(u32x4*)(dst + 8) = o1;
;     }
;     __syncthreads();
; }
; __device__ __forceinline__ void convert_layer(const Args& A, Frame& F, int l) {
;     refresh(F);
;     constexpr int NT = 2 * 16 * 44 + 2 * 44 * 8 + 16 * 56 + 3 * 16 * 8;
;     const int nmy = (NT - F.bid + F.G - 1) / F.G;
;     f32x4 v[4];
;     { CvtMat m; int tt; cvt_pick(A, F, l, F.bid, m, tt); cvt_load(F, m, tt, v); }
;     for (int j = 0; j < nmy; ++j) {
;         const int it = F.bid + j * F.G, itn = (j + 1 < nmy) ? it + F.G : it;
;         f32x4 vn[4];
;         { CvtMat mn; int ttn; cvt_pick(A, F, l, itn, mn, ttn); cvt_load(F, mn, ttn, vn); }
;         { CvtMat m; int tt; cvt_pick(A, F, l, it, m, tt); cvt_store(F, m, tt, v); }
; #pragma unroll
;         for (int i = 0; i < 4; ++i) v[i] = vn[i];
;     }
.LBB0_607:
	s_nop 0
	ds_write2_b32 v41, v2, v3 offset1:1
	ds_write2_b32 v41, v4, v5 offset0:2 offset1:3
	v_add_u32_e32 v2, 0x2040, v41
	s_nop 0
	ds_write2_b32 v2, v6, v7 offset1:1
	v_add_u32_e32 v2, 0x2048, v41
	ds_write2_b32 v2, v8, v9 offset1:1
	v_add_u32_e32 v2, 0x4080, v41
	s_nop 0
	ds_write2_b32 v2, v10, v11 offset1:1
	v_add_u32_e32 v2, 0x4088, v41
	ds_write2_b32 v2, v12, v13 offset1:1
	v_add_u32_e32 v2, 0x60c0, v41
	s_nop 0
	ds_write2_b32 v2, v14, v15 offset1:1
	v_add_u32_e32 v2, 0x60c8, v41
	v_add_u32_e32 v4, 0x400, v37
	v_add_u32_e32 v6, 0x800, v37
	ds_write2_b32 v2, v16, v17 offset1:1
	s_waitcnt lgkmcnt(0)
	s_barrier
	ds_read2_b32 v[2:3], v37 offset1:129
	ds_read2_b32 v[4:5], v4 offset0:2 offset1:131
	ds_read2_b32 v[6:7], v6 offset0:4 offset1:133
	v_add_u32_e32 v8, 0xc00, v37
	ds_read2_b32 v[8:9], v8 offset0:6 offset1:135
	v_add_u32_e32 v10, 0x1000, v37
	ds_read2_b32 v[10:11], v10 offset0:8 offset1:137
	s_waitcnt lgkmcnt(4)
	v_cvt_pk_bf16_f32 v2, v2, v3
	s_waitcnt lgkmcnt(3)
	v_cvt_pk_bf16_f32 v3, v4, v5
	s_waitcnt lgkmcnt(2)
	v_cvt_pk_bf16_f32 v4, v6, v7
	v_add_u32_e32 v7, 0x1400, v37
	s_waitcnt lgkmcnt(1)
	v_cvt_pk_bf16_f32 v5, v8, v9
	ds_read2_b32 v[8:9], v7 offset0:10 offset1:139
	v_add_u32_e32 v7, 0x1800, v37
	s_waitcnt lgkmcnt(1)
	v_cvt_pk_bf16_f32 v6, v10, v11
	ds_read2_b32 v[10:11], v7 offset0:12 offset1:141
	v_add_u32_e32 v7, 0x1c00, v37
	ds_read2_b32 v[12:13], v7 offset0:14 offset1:143
	v_cvt_f32_ubyte0_e32 v7, s10
	v_rcp_iflag_f32_e32 v14, v7
	s_waitcnt lgkmcnt(2)
	v_cvt_pk_bf16_f32 v7, v8, v9
	s_waitcnt lgkmcnt(1)
	v_cvt_pk_bf16_f32 v8, v10, v11
	s_add_u32 s4, s30, s4
	v_mul_f32_e32 v10, 0x4f7ffffe, v14
	v_cvt_u32_f32_e32 v10, v10
	s_addc_u32 s5, s31, s5
	s_and_b32 s8, s14, 13
	s_cmp_eq_u32 s8, 1
	s_cselect_b32 s9, s22, 0x400
	s_sub_i32 s13, 0, s10
	v_readfirstlane_b32 s14, v10
	s_mul_i32 s13, s13, s14
	s_add_i32 s8, s11, s26
	s_mul_hi_u32 s13, s14, s13
	s_abs_i32 s12, s8
	s_add_i32 s14, s14, s13
	s_mul_hi_u32 s13, s12, s14
	s_mul_i32 s14, s13, s10
	s_sub_i32 s12, s12, s14
	s_ashr_i32 s11, s8, 31
	s_add_i32 s14, s13, 1
	s_sub_i32 s15, s12, s10
	s_cmp_ge_u32 s12, s10
	s_cselect_b32 s13, s14, s13
	s_cselect_b32 s12, s15, s12
	s_add_i32 s14, s13, 1
	s_cmp_ge_u32 s12, s10
	s_cselect_b32 s12, s14, s13
	s_xor_b32 s12, s12, s11
	s_sub_i32 s11, s12, s11
	s_mul_i32 s10, s10, s11
	s_sub_i32 s10, s8, s10
	v_lshl_add_u32 v10, s10, 7, v36
	s_lshl_b32 s8, s11, 6
	v_mad_i64_i32 v[10:11], s[10:11], s9, v10, 0
	v_lshl_add_u64 v[10:11], v[10:11], 1, s[4:5]
	s_ashr_i32 s9, s8, 31
	v_lshl_add_u64 v[10:11], s[8:9], 1, v[10:11]
	s_waitcnt lgkmcnt(0)
	v_cvt_pk_bf16_f32 v9, v12, v13
	v_lshl_add_u64 v[10:11], v[10:11], 0, v[0:1]
	s_lshl_b32 s98, s34, 1
	s_add_i32 s98, s98, s26
	s_min_i32 s98, s98, 0xd3f
	s_movk_i32 s99, 0x038
	s_mov_b32 s100, 0
	s_cmpk_ge_i32 s98, 704
	s_cselect_b32 s99, 0x140, s99
	s_cselect_b32 s100, 704, s100
	s_cmpk_ge_i32 s98, 1056
	s_cselect_b32 s99, 0x48, s99
	s_cselect_b32 s100, 1056, s100
	s_cmpk_ge_i32 s98, 1760
	s_cselect_b32 s99, 0x150, s99
	s_cselect_b32 s100, 1760, s100
	s_cmpk_ge_i32 s98, 2112
	s_cselect_b32 s99, 0x258, s99
	s_cselect_b32 s100, 2112, s100
	s_cmpk_ge_i32 s98, 3008
	s_cselect_b32 s99, 0x368, s99
	s_cselect_b32 s100, 3008, s100
	s_cmpk_ge_i32 s98, 3136
	s_cselect_b32 s99, 0x398, s99
	s_cselect_b32 s100, 3136, s100
	s_cmpk_ge_i32 s98, 3264
	s_cselect_b32 s99, 0x3a0, s99
	s_cselect_b32 s100, 3264, s100
	s_sub_i32 s98, s98, s100
	s_and_b32 m0, s99, 0xff
	s_load_dwordx2 s[100:101], s[46:47], m0
	s_lshr_b32 s99, s99, 8
	s_cmp_eq_u32 s99, 0
	s_cbranch_scc1 .Lcw_gu
	s_cmp_eq_u32 s99, 2
	s_cbranch_scc1 .Lcw_win
	s_cmp_eq_u32 s99, 1
	s_mov_b32 s99, 0x400000
	s_cselect_b32 s99, 0xb00000, s99
	s_mul_i32 s99, s99, s44
	s_lshr_b32 m0, s98, 3
	s_and_b32 s98, s98, 7
	s_lshl_b32 s98, s98, 9
	s_lshl_b32 m0, m0, 18
	s_add_i32 s98, s98, m0
	s_add_i32 s98, s98, s99
	s_movk_i32 s99, 0x1000
	s_branch .Lcw_go
.Lcw_gu:
	s_mul_i32 m0, s98, 1490
	s_lshr_b32 m0, m0, 16
	s_mul_i32 s99, m0, 44
	s_sub_i32 s99, s98, s99
	s_mul_i32 s98, m0, 0x160000
	s_and_b32 m0, s99, 1
	s_mul_i32 m0, m0, 0x2c00
	s_add_i32 s98, s98, m0
	s_lshr_b32 m0, s99, 1
	s_lshl_b32 m0, m0, 9
	s_add_i32 s98, s98, m0
	s_mul_i32 m0, s44, 0x1600000
	s_add_i32 s98, s98, m0
	s_movk_i32 s99, 0x5800
	s_branch .Lcw_go
.Lcw_win:
	s_mul_i32 m0, s98, 1171
	s_lshr_b32 m0, m0, 16
	s_mul_i32 s99, m0, 56
	s_sub_i32 s99, s98, s99
	s_mul_i32 s98, m0, 0x1c0000
	s_lshl_b32 s99, s99, 9
	s_add_i32 s98, s98, s99
	s_mul_i32 m0, s44, 0x1c00000
	s_add_i32 s98, s98, m0
	s_movk_i32 s99, 0x7000
.Lcw_go:
	v_lshrrev_b32_e32 v190, 3, v138
	v_mul_lo_u32 v190, v190, s99
	v_and_b32_e32 v191, 7, v138
	v_lshl_add_u32 v190, v191, 6, v190
	v_add_u32_e32 v190, s98, v190
	s_waitcnt lgkmcnt(0)
	global_load_dword v189, v190, s[100:101]
	s_add_i32 s26, s26, s34
	global_store_dwordx4 v[10:11], v[2:5], off
	global_store_dwordx4 v[10:11], v[6:9], off offset:16
	s_cmp_lg_u32 s2, s20
	s_waitcnt vmcnt(6)
	v_mov_b32_e32 v2, v22
	v_mov_b32_e32 v3, v23
	v_mov_b32_e32 v4, v24
	v_mov_b32_e32 v5, v25
	s_waitcnt vmcnt(5)
	v_mov_b32_e32 v6, v18
	v_mov_b32_e32 v7, v19
	v_mov_b32_e32 v8, v20
	v_mov_b32_e32 v9, v21
	s_waitcnt vmcnt(4)
	v_mov_b32_e32 v10, v30
	v_mov_b32_e32 v11, v31
	v_mov_b32_e32 v12, v32
	v_mov_b32_e32 v13, v33
	s_waitcnt vmcnt(3)
	v_mov_b32_e32 v14, v26
	v_mov_b32_e32 v15, v27
	v_mov_b32_e32 v16, v28
	v_mov_b32_e32 v17, v29
	s_barrier
	s_cbranch_scc0 .LBB0_691

; __device__ __forceinline__ unsigned pk2(float lo, float hi) { const f32x2_t v = {lo, hi}; const bf16v2_t b = __builtin_convertvector(v, bf16v2_t); return __builtin_bit_cast(unsigned, b); }
; __device__ __forceinline__ void refresh(Frame& F) { int t = threadIdx.x; asm volatile("" : "+v"(t)); F.tid = t; F.lane = t & 63; F.wave = __builtin_amdgcn_readfirstlane(t >> 6); }
; __device__ __forceinline__ void init_phase(const Args& A, Frame& F) {
;     refresh(F);
;     const size_t nunits = (size_t)MROWS * D / 4;
;     for (size_t uidx = (size_t)F.bid * NTHREADS + F.tid; uidx < nunits; uidx += (size_t)F.G * NTHREADS) {
;         const size_t row = uidx >> 8; const int c4 = (int)(uidx & 255) * 4;
;         const int b = (int)(row / TB), p = (int)(row - (size_t)b * TB);
;         const float* src = p < CTXL ? GIN(2) + ((size_t)b * CTXL + p) * D + c4 : GIN(0) + ((size_t)b * SEQ + (p - CTXL)) * D + c4;
;         { const f32x4 xv = *(const f32x4*)src; u32x2 o; o.x = pk2(xv[0], xv[1]); o.y = pk2(xv[2], xv[3]); *(u32x2*)(WSB(WS_R) + row * D + c4) = o; }
;     }
.LBB0_714:
	v_mov_b32_e32 v4, v138
	s_ashr_i32 s39, s38, 31
	s_lshl_b64 s[4:5], s[38:39], 9
	v_ashrrev_i32_e32 v5, 31, v4
	v_lshl_add_u64 v[2:3], s[4:5], 0, v[4:5]
	s_mov_b64 s[4:5], 0x480000
	v_cmp_gt_u64_e32 vcc, s[4:5], v[2:3]
	s_and_saveexec_b64 s[4:5], vcc
	s_cbranch_execz .LBB0_721
	s_ashr_i32 s37, s36, 31
	s_lshl_b64 s[6:7], s[36:37], 3
	s_add_u32 s6, s0, s6
	s_addc_u32 s7, s1, s7
	s_add_u32 s8, s30, 0x36c8000
	s_addc_u32 s9, s31, 0
	s_cmpk_lg_i32 s34, 0x100
	s_cbranch_scc1 .Lini_orig
	s_load_dwordx2 s[10:11], s[6:7], 0x0
	s_load_dwordx2 s[12:13], s[6:7], 0x10
	v_readfirstlane_b32 s14, v138
	s_lshr_b32 s14, s14, 8
	s_lshl_b32 s15, s38, 1
	s_add_i32 s14, s14, s15
	v_and_b32_e32 v190, 0xff, v138
	v_lshlrev_b32_e32 v191, 3, v190
	v_lshlrev_b32_e32 v190, 4, v190
	s_mov_b32 s15, 0
	s_waitcnt lgkmcnt(0)
.Lini_loop:
	s_add_i32 s2, s15, 0
	s_lshl_b32 s2, s2, 9
	s_add_i32 s2, s2, s14
	s_lshr_b32 s26, s2, 8
	s_mul_hi_u32 s26, s26, 0x38e38e39
	s_lshr_b32 s26, s26, 1
	s_mul_i32 s27, s26, 0x900
	s_sub_i32 s27, s2, s27
	s_lshl_b32 s40, s26, 8
	s_add_i32 s40, s40, s27
	s_lshl_b32 s41, s26, 11
	s_add_i32 s41, s41, s27
	s_addk_i32 s41, 0xff00
	s_cmp_lt_u32 s27, 0x100
	s_cselect_b32 s40, s40, s41
	s_cselect_b32 s98, s12, s10
	s_cselect_b32 s99, s13, s11
	s_lshl_b32 s40, s40, 12
	s_add_u32 s98, s98, s40
	s_addc_u32 s99, s99, 0
	global_load_dwordx4 v[192:195], v190, s[98:99]
	s_add_i32 s2, s15, 1
	s_lshl_b32 s2, s2, 9
	s_add_i32 s2, s2, s14
	s_lshr_b32 s26, s2, 8
	s_mul_hi_u32 s26, s26, 0x38e38e39
	s_lshr_b32 s26, s26, 1
	s_mul_i32 s27, s26, 0x900
	s_sub_i32 s27, s2, s27
	s_lshl_b32 s40, s26, 8
	s_add_i32 s40, s40, s27
	s_lshl_b32 s41, s26, 11
	s_add_i32 s41, s41, s27
	s_addk_i32 s41, 0xff00
	s_cmp_lt_u32 s27, 0x100
	s_cselect_b32 s40, s40, s41
	s_cselect_b32 s98, s12, s10
	s_cselect_b32 s99, s13, s11
	s_lshl_b32 s40, s40, 12
	s_add_u32 s98, s98, s40
	s_addc_u32 s99, s99, 0
	global_load_dwordx4 v[196:199], v190, s[98:99]
	s_add_i32 s2, s15, 2
	s_lshl_b32 s2, s2, 9
	s_add_i32 s2, s2, s14
	s_lshr_b32 s26, s2, 8
	s_mul_hi_u32 s26, s26, 0x38e38e39
	s_lshr_b32 s26, s26, 1
	s_mul_i32 s27, s26, 0x900
	s_sub_i32 s27, s2, s27
	s_lshl_b32 s40, s26, 8
	s_add_i32 s40, s40, s27
	s_lshl_b32 s41, s26, 11
	s_add_i32 s41, s41, s27
	s_addk_i32 s41, 0xff00
	s_cmp_lt_u32 s27, 0x100
	s_cselect_b32 s40, s40, s41
	s_cselect_b32 s98, s12, s10
	s_cselect_b32 s99, s13, s11
	s_lshl_b32 s40, s40, 12
	s_add_u32 s98, s98, s40
	s_addc_u32 s99, s99, 0
	global_load_dwordx4 v[200:203], v190, s[98:99]
	s_add_i32 s2, s15, 3
	s_lshl_b32 s2, s2, 9
	s_add_i32 s2, s2, s14
	s_lshr_b32 s26, s2, 8
	s_mul_hi_u32 s26, s26, 0x38e38e39
	s_lshr_b32 s26, s26, 1
	s_mul_i32 s27, s26, 0x900
	s_sub_i32 s27, s2, s27
	s_lshl_b32 s40, s26, 8
	s_add_i32 s40, s40, s27
	s_lshl_b32 s41, s26, 11
	s_add_i32 s41, s41, s27
	s_addk_i32 s41, 0xff00
	s_cmp_lt_u32 s27, 0x100
	s_cselect_b32 s40, s40, s41
	s_cselect_b32 s98, s12, s10
	s_cselect_b32 s99, s13, s11
	s_lshl_b32 s40, s40, 12
	s_add_u32 s98, s98, s40
	s_addc_u32 s99, s99, 0
	global_load_dwordx4 v[204:207], v190, s[98:99]
	s_add_i32 s2, s15, 4
	s_lshl_b32 s2, s2, 9
	s_add_i32 s2, s2, s14
	s_lshr_b32 s26, s2, 8
	s_mul_hi_u32 s26, s26, 0x38e38e39
	s_lshr_b32 s26, s26, 1
	s_mul_i32 s27, s26, 0x900
	s_sub_i32 s27, s2, s27
	s_lshl_b32 s40, s26, 8
	s_add_i32 s40, s40, s27
	s_lshl_b32 s41, s26, 11
	s_add_i32 s41, s41, s27
	s_addk_i32 s41, 0xff00
	s_cmp_lt_u32 s27, 0x100
	s_cselect_b32 s40, s40, s41
	s_cselect_b32 s98, s12, s10
	s_cselect_b32 s99, s13, s11
	s_lshl_b32 s40, s40, 12
	s_add_u32 s98, s98, s40
	s_addc_u32 s99, s99, 0
	global_load_dwordx4 v[208:211], v190, s[98:99]
	s_add_i32 s2, s15, 5
	s_lshl_b32 s2, s2, 9
	s_add_i32 s2, s2, s14
	s_lshr_b32 s26, s2, 8
	s_mul_hi_u32 s26, s26, 0x38e38e39
	s_lshr_b32 s26, s26, 1
	s_mul_i32 s27, s26, 0x900
	s_sub_i32 s27, s2, s27
	s_lshl_b32 s40, s26, 8
	s_add_i32 s40, s40, s27
	s_lshl_b32 s41, s26, 11
	s_add_i32 s41, s41, s27
	s_addk_i32 s41, 0xff00
	s_cmp_lt_u32 s27, 0x100
	s_cselect_b32 s40, s40, s41
	s_cselect_b32 s98, s12, s10
	s_cselect_b32 s99, s13, s11
	s_lshl_b32 s40, s40, 12
	s_add_u32 s98, s98, s40
	s_addc_u32 s99, s99, 0
	global_load_dwordx4 v[212:215], v190, s[98:99]
	s_add_i32 s2, s15, 6
	s_lshl_b32 s2, s2, 9
	s_add_i32 s2, s2, s14
	s_lshr_b32 s26, s2, 8
	s_mul_hi_u32 s26, s26, 0x38e38e39
	s_lshr_b32 s26, s26, 1
	s_mul_i32 s27, s26, 0x900
	s_sub_i32 s27, s2, s27
	s_lshl_b32 s40, s26, 8
	s_add_i32 s40, s40, s27
	s_lshl_b32 s41, s26, 11
	s_add_i32 s41, s41, s27
	s_addk_i32 s41, 0xff00
	s_cmp_lt_u32 s27, 0x100
	s_cselect_b32 s40, s40, s41
	s_cselect_b32 s98, s12, s10
	s_cselect_b32 s99, s13, s11
	s_lshl_b32 s40, s40, 12
	s_add_u32 s98, s98, s40
	s_addc_u32 s99, s99, 0
	global_load_dwordx4 v[216:219], v190, s[98:99]
	s_add_i32 s2, s15, 7
	s_lshl_b32 s2, s2, 9
	s_add_i32 s2, s2, s14
	s_lshr_b32 s26, s2, 8
	s_mul_hi_u32 s26, s26, 0x38e38e39
	s_lshr_b32 s26, s26, 1
	s_mul_i32 s27, s26, 0x900
	s_sub_i32 s27, s2, s27
	s_lshl_b32 s40, s26, 8
	s_add_i32 s40, s40, s27
	s_lshl_b32 s41, s26, 11
	s_add_i32 s41, s41, s27
	s_addk_i32 s41, 0xff00
	s_cmp_lt_u32 s27, 0x100
	s_cselect_b32 s40, s40, s41
	s_cselect_b32 s98, s12, s10
	s_cselect_b32 s99, s13, s11
	s_lshl_b32 s40, s40, 12
	s_add_u32 s98, s98, s40
	s_addc_u32 s99, s99, 0
	global_load_dwordx4 v[220:223], v190, s[98:99]
	s_add_i32 s2, s15, 8
	s_lshl_b32 s2, s2, 9
	s_add_i32 s2, s2, s14
	s_lshr_b32 s26, s2, 8
	s_mul_hi_u32 s26, s26, 0x38e38e39
	s_lshr_b32 s26, s26, 1
	s_mul_i32 s27, s26, 0x900
	s_sub_i32 s27, s2, s27
	s_lshl_b32 s40, s26, 8
	s_add_i32 s40, s40, s27
	s_lshl_b32 s41, s26, 11
	s_add_i32 s41, s41, s27
; __device__ __forceinline__ unsigned pk2(float lo, float hi) { const f32x2_t v = {lo, hi}; const bf16v2_t b = __builtin_convertvector(v, bf16v2_t); return __builtin_bit_cast(unsigned, b); }
; __device__ __forceinline__ void refresh(Frame& F) { int t = threadIdx.x; asm volatile("" : "+v"(t)); F.tid = t; F.lane = t & 63; F.wave = __builtin_amdgcn_readfirstlane(t >> 6); }
; __device__ __forceinline__ void init_phase(const Args& A, Frame& F) {
;     refresh(F);
;     const size_t nunits = (size_t)MROWS * D / 4;
;     for (size_t uidx = (size_t)F.bid * NTHREADS + F.tid; uidx < nunits; uidx += (size_t)F.G * NTHREADS) {
;         const size_t row = uidx >> 8; const int c4 = (int)(uidx & 255) * 4;
;         const int b = (int)(row / TB), p = (int)(row - (size_t)b * TB);
;         const float* src = p < CTXL ? GIN(2) + ((size_t)b * CTXL + p) * D + c4 : GIN(0) + ((size_t)b * SEQ + (p - CTXL)) * D + c4;
;         { const f32x4 xv = *(const f32x4*)src; u32x2 o; o.x = pk2(xv[0], xv[1]); o.y = pk2(xv[2], xv[3]); *(u32x2*)(WSB(WS_R) + row * D + c4) = o; }
;     }
	s_addk_i32 s41, 0xff00
	s_cmp_lt_u32 s27, 0x100
	s_cselect_b32 s40, s40, s41
	s_cselect_b32 s98, s12, s10
	s_cselect_b32 s99, s13, s11
	s_lshl_b32 s40, s40, 12
	s_add_u32 s98, s98, s40
	s_addc_u32 s99, s99, 0
	global_load_dwordx4 v[224:227], v190, s[98:99]
	s_add_i32 s2, s15, 9
	s_lshl_b32 s2, s2, 9
	s_add_i32 s2, s2, s14
	s_lshr_b32 s26, s2, 8
	s_mul_hi_u32 s26, s26, 0x38e38e39
	s_lshr_b32 s26, s26, 1
	s_mul_i32 s27, s26, 0x900
	s_sub_i32 s27, s2, s27
	s_lshl_b32 s40, s26, 8
	s_add_i32 s40, s40, s27
	s_lshl_b32 s41, s26, 11
	s_add_i32 s41, s41, s27
	s_addk_i32 s41, 0xff00
	s_cmp_lt_u32 s27, 0x100
	s_cselect_b32 s40, s40, s41
	s_cselect_b32 s98, s12, s10
	s_cselect_b32 s99, s13, s11
	s_lshl_b32 s40, s40, 12
	s_add_u32 s98, s98, s40
	s_addc_u32 s99, s99, 0
	global_load_dwordx4 v[228:231], v190, s[98:99]
	s_add_i32 s2, s15, 10
	s_lshl_b32 s2, s2, 9
	s_add_i32 s2, s2, s14
	s_lshr_b32 s26, s2, 8
	s_mul_hi_u32 s26, s26, 0x38e38e39
	s_lshr_b32 s26, s26, 1
	s_mul_i32 s27, s26, 0x900
	s_sub_i32 s27, s2, s27
	s_lshl_b32 s40, s26, 8
	s_add_i32 s40, s40, s27
	s_lshl_b32 s41, s26, 11
	s_add_i32 s41, s41, s27
	s_addk_i32 s41, 0xff00
	s_cmp_lt_u32 s27, 0x100
	s_cselect_b32 s40, s40, s41
	s_cselect_b32 s98, s12, s10
	s_cselect_b32 s99, s13, s11
	s_lshl_b32 s40, s40, 12
	s_add_u32 s98, s98, s40
	s_addc_u32 s99, s99, 0
	global_load_dwordx4 v[232:235], v190, s[98:99]
	s_add_i32 s2, s15, 11
	s_lshl_b32 s2, s2, 9
	s_add_i32 s2, s2, s14
	s_lshr_b32 s26, s2, 8
	s_mul_hi_u32 s26, s26, 0x38e38e39
	s_lshr_b32 s26, s26, 1
	s_mul_i32 s27, s26, 0x900
	s_sub_i32 s27, s2, s27
	s_lshl_b32 s40, s26, 8
	s_add_i32 s40, s40, s27
	s_lshl_b32 s41, s26, 11
	s_add_i32 s41, s41, s27
	s_addk_i32 s41, 0xff00
	s_cmp_lt_u32 s27, 0x100
	s_cselect_b32 s40, s40, s41
	s_cselect_b32 s98, s12, s10
	s_cselect_b32 s99, s13, s11
	s_lshl_b32 s40, s40, 12
	s_add_u32 s98, s98, s40
	s_addc_u32 s99, s99, 0
	global_load_dwordx4 v[236:239], v190, s[98:99]
	s_waitcnt vmcnt(11)
	v_cvt_pk_bf16_f32 v192, v192, v193
	v_cvt_pk_bf16_f32 v193, v194, v195
	s_add_i32 s2, s15, 0
	s_lshl_b32 s2, s2, 9
	s_add_i32 s2, s2, s14
	s_lshl_b32 s2, s2, 11
	s_add_u32 s98, s8, s2
	s_addc_u32 s99, s9, 0
	global_store_dwordx2 v191, v[192:193], s[98:99]
	s_waitcnt vmcnt(11)
	v_cvt_pk_bf16_f32 v196, v196, v197
	v_cvt_pk_bf16_f32 v197, v198, v199
	s_add_i32 s2, s15, 1
	s_lshl_b32 s2, s2, 9
	s_add_i32 s2, s2, s14
	s_lshl_b32 s2, s2, 11
	s_add_u32 s98, s8, s2
	s_addc_u32 s99, s9, 0
	global_store_dwordx2 v191, v[196:197], s[98:99]
	s_waitcnt vmcnt(11)
	v_cvt_pk_bf16_f32 v200, v200, v201
	v_cvt_pk_bf16_f32 v201, v202, v203
	s_add_i32 s2, s15, 2
	s_lshl_b32 s2, s2, 9
	s_add_i32 s2, s2, s14
	s_lshl_b32 s2, s2, 11
	s_add_u32 s98, s8, s2
	s_addc_u32 s99, s9, 0
	global_store_dwordx2 v191, v[200:201], s[98:99]
	s_waitcnt vmcnt(11)
	v_cvt_pk_bf16_f32 v204, v204, v205
	v_cvt_pk_bf16_f32 v205, v206, v207
	s_add_i32 s2, s15, 3
	s_lshl_b32 s2, s2, 9
	s_add_i32 s2, s2, s14
	s_lshl_b32 s2, s2, 11
	s_add_u32 s98, s8, s2
	s_addc_u32 s99, s9, 0
	global_store_dwordx2 v191, v[204:205], s[98:99]
	s_waitcnt vmcnt(11)
	v_cvt_pk_bf16_f32 v208, v208, v209
	v_cvt_pk_bf16_f32 v209, v210, v211
	s_add_i32 s2, s15, 4
	s_lshl_b32 s2, s2, 9
	s_add_i32 s2, s2, s14
	s_lshl_b32 s2, s2, 11
	s_add_u32 s98, s8, s2
	s_addc_u32 s99, s9, 0
	global_store_dwordx2 v191, v[208:209], s[98:99]
	s_waitcnt vmcnt(11)
	v_cvt_pk_bf16_f32 v212, v212, v213
	v_cvt_pk_bf16_f32 v213, v214, v215
	s_add_i32 s2, s15, 5
	s_lshl_b32 s2, s2, 9
	s_add_i32 s2, s2, s14
	s_lshl_b32 s2, s2, 11
	s_add_u32 s98, s8, s2
	s_addc_u32 s99, s9, 0
	global_store_dwordx2 v191, v[212:213], s[98:99]
	s_waitcnt vmcnt(11)
	v_cvt_pk_bf16_f32 v216, v216, v217
	v_cvt_pk_bf16_f32 v217, v218, v219
	s_add_i32 s2, s15, 6
	s_lshl_b32 s2, s2, 9
	s_add_i32 s2, s2, s14
	s_lshl_b32 s2, s2, 11
	s_add_u32 s98, s8, s2
	s_addc_u32 s99, s9, 0
	global_store_dwordx2 v191, v[216:217], s[98:99]
	s_waitcnt vmcnt(11)
	v_cvt_pk_bf16_f32 v220, v220, v221
	v_cvt_pk_bf16_f32 v221, v222, v223
	s_add_i32 s2, s15, 7
	s_lshl_b32 s2, s2, 9
	s_add_i32 s2, s2, s14
	s_lshl_b32 s2, s2, 11
	s_add_u32 s98, s8, s2
	s_addc_u32 s99, s9, 0
	global_store_dwordx2 v191, v[220:221], s[98:99]
	s_waitcnt vmcnt(11)
	v_cvt_pk_bf16_f32 v224, v224, v225
	v_cvt_pk_bf16_f32 v225, v226, v227
	s_add_i32 s2, s15, 8
	s_lshl_b32 s2, s2, 9
	s_add_i32 s2, s2, s14
	s_lshl_b32 s2, s2, 11
	s_add_u32 s98, s8, s2
	s_addc_u32 s99, s9, 0
	global_store_dwordx2 v191, v[224:225], s[98:99]
	s_waitcnt vmcnt(11)
	v_cvt_pk_bf16_f32 v228, v228, v229
	v_cvt_pk_bf16_f32 v229, v230, v231
	s_add_i32 s2, s15, 9
	s_lshl_b32 s2, s2, 9
	s_add_i32 s2, s2, s14
	s_lshl_b32 s2, s2, 11
	s_add_u32 s98, s8, s2
	s_addc_u32 s99, s9, 0
	global_store_dwordx2 v191, v[228:229], s[98:99]
	s_waitcnt vmcnt(11)
	v_cvt_pk_bf16_f32 v232, v232, v233
	v_cvt_pk_bf16_f32 v233, v234, v235
	s_add_i32 s2, s15, 10
	s_lshl_b32 s2, s2, 9
	s_add_i32 s2, s2, s14
	s_lshl_b32 s2, s2, 11
	s_add_u32 s98, s8, s2
	s_addc_u32 s99, s9, 0
	global_store_dwordx2 v191, v[232:233], s[98:99]
	s_waitcnt vmcnt(11)
	v_cvt_pk_bf16_f32 v236, v236, v237
	v_cvt_pk_bf16_f32 v237, v238, v239
	s_add_i32 s2, s15, 11
	s_lshl_b32 s2, s2, 9
	s_add_i32 s2, s2, s14
	s_lshl_b32 s2, s2, 11
	s_add_u32 s98, s8, s2
	s_addc_u32 s99, s9, 0
	global_store_dwordx2 v191, v[236:237], s[98:99]
	s_add_i32 s15, s15, 12
	s_cmp_lt_u32 s15, 36
	s_cbranch_scc1 .Lini_loop
	s_branch .LBB0_721
.Lini_orig:
	s_ashr_i32 s35, s34, 31
	s_lshl_b64 s[12:13], s[38:39], 11
	s_lshl_b64 s[10:11], s[34:35], 9
	v_lshl_add_u64 v[6:7], v[4:5], 2, s[12:13]
	s_lshl_b64 s[12:13], s[34:35], 11
	s_mov_b64 s[14:15], 0
	s_branch .LBB0_717
